# P9 hand-written: each of the 2048 waves combines one 256-element quarter row (13 loads) instead of 512 waves doing a whole row (52 loads)
# speedup vs baseline: 1.0027x; 1.0027x over previous
; #define FRESH_IDS() const int tid = fresh_tid(), lane = tid & 63, wid = __builtin_amdgcn_readfirstlane(tid >> 6); (void)tid; (void)lane; (void)wid
; __device__ __forceinline__ void sample_combine(const float* gate, const float* part, int nsk, int srow, f32x4 (&v)[4], int lane) {
; #pragma unroll
;     for (int j = 0; j < 4; ++j) { const int c4 = lane + 64 * j; f32x4 a = (f32x4){0.f, 0.f, 0.f, 0.f};
;         for (int k = 0; k < nsk; ++k) a += *((const f32x4*)(part + ((size_t)k * 512 + srow) * DM) + c4);
;         v[j] = v[j] + *((const f32x4*)gate + c4) * a; }
; }
; __device__ __forceinline__ void row_load_bf16(const bf16_t* row, f32x4 (&v)[4], int lane) {
; #pragma unroll
;     for (int j = 0; j < 4; ++j) { const u32x2 w = *((const u32x2*)row + lane + 64 * j);
;         v[j] = (f32x4){__uint_as_float(w.x << 16), __uint_as_float(w.x & 0xffff0000u), __uint_as_float(w.y << 16), __uint_as_float(w.y & 0xffff0000u)}; }
; }
; __global__ void __launch_bounds__(512, 2) mega_fwd(Args a) {
;     ...
;     { FRESH_IDS();
;         for (int sr = bx * 8 + wid; sr < MS; sr += G * 8) { const int b16 = 8 + (sr >> 6); f32x4 v[4];
;             row_load_bf16(X1B + (size_t)(MP + sr) * DM, v, lane);
;             sample_combine(MOD + (size_t)b16 * 6144 + 5120, PART, 11, sr, v, lane);
; #pragma unroll
;             for (int j = 0; j < 4; ++j) *((f32x4*)(out + (size_t)(MP + sr) * DM) + lane + 64 * j) = v[j]; } }
.LBB0_1320:
	s_or_b64 exec, exec, s[0:1]
	s_waitcnt lgkmcnt(0)
	s_barrier
	v_readlane_b32 s3, v238, 46
	s_lshr_b32 s3, s3, 3
	v_readfirstlane_b32 s0, v211
	s_ashr_i32 s0, s0, 6
	s_lshr_b32 s1, s0, 2
	s_lshl_b32 s1, s1, 8
	s_add_i32 s6, s1, s3
	s_and_b32 s7, s0, 3
	v_and_b32_e32 v0, 63, v211
	v_lshlrev_b32_e32 v1, 4, v0
	v_lshlrev_b32_e32 v2, 3, v0
	s_lshl_b32 s8, s6, 12
	s_lshl_b32 s9, s7, 10
	s_add_i32 s8, s8, s9
	s_add_u32 s10, s30, 0x1aa00000
	s_addc_u32 s11, s31, 0
	s_add_u32 s10, s10, s8
	s_addc_u32 s11, s11, 0
	global_load_dwordx4 v[8:11], v1, s[10:11]
	s_add_u32 s10, s10, 0x200000
	s_addc_u32 s11, s11, 0
	global_load_dwordx4 v[12:15], v1, s[10:11]
	s_add_u32 s10, s10, 0x200000
	s_addc_u32 s11, s11, 0
	global_load_dwordx4 v[16:19], v1, s[10:11]
	s_add_u32 s10, s10, 0x200000
	s_addc_u32 s11, s11, 0
	global_load_dwordx4 v[20:23], v1, s[10:11]
	s_add_u32 s10, s10, 0x200000
	s_addc_u32 s11, s11, 0
	global_load_dwordx4 v[24:27], v1, s[10:11]
	s_add_u32 s10, s10, 0x200000
	s_addc_u32 s11, s11, 0
	global_load_dwordx4 v[28:31], v1, s[10:11]
	s_add_u32 s10, s10, 0x200000
	s_addc_u32 s11, s11, 0
	global_load_dwordx4 v[32:35], v1, s[10:11]
	s_add_u32 s10, s10, 0x200000
	s_addc_u32 s11, s11, 0
	global_load_dwordx4 v[36:39], v1, s[10:11]
	s_add_u32 s10, s10, 0x200000
	s_addc_u32 s11, s11, 0
	global_load_dwordx4 v[40:43], v1, s[10:11]
	s_add_u32 s10, s10, 0x200000
	s_addc_u32 s11, s11, 0
	global_load_dwordx4 v[44:47], v1, s[10:11]
	s_add_u32 s10, s10, 0x200000
	s_addc_u32 s11, s11, 0
	global_load_dwordx4 v[48:51], v1, s[10:11]
	s_add_i32 s12, s6, 0x8000
	s_lshl_b32 s13, s12, 11
	s_lshl_b32 s14, s7, 9
	s_add_i32 s13, s13, s14
	s_add_u32 s14, s30, 0x15900000
	s_addc_u32 s15, s31, 0
	s_add_u32 s14, s14, s13
	s_addc_u32 s15, s15, 0
	global_load_dwordx2 v[52:53], v2, s[14:15]
	s_lshr_b32 s16, s6, 6
	s_add_i32 s16, s16, 8
	s_mul_i32 s16, s16, 0x6000
	s_add_i32 s16, s16, 0x5000
	s_add_i32 s16, s16, s9
	s_add_u32 s18, s30, s16
	s_addc_u32 s19, s31, 0
	global_load_dwordx4 v[56:59], v1, s[18:19]
	s_lshl_b32 s13, s12, 12
	s_lshr_b32 s14, s12, 20
	s_add_i32 s13, s13, s9
	s_add_u32 s20, s28, s13
	s_addc_u32 s21, s29, s14
	s_waitcnt vmcnt(11)
	v_pk_add_f32 v[8:9], v[8:9], v[12:13]
	v_pk_add_f32 v[10:11], v[10:11], v[14:15]
	s_waitcnt vmcnt(10)
	v_pk_add_f32 v[8:9], v[8:9], v[16:17]
	v_pk_add_f32 v[10:11], v[10:11], v[18:19]
	s_waitcnt vmcnt(9)
	v_pk_add_f32 v[8:9], v[8:9], v[20:21]
	v_pk_add_f32 v[10:11], v[10:11], v[22:23]
	s_waitcnt vmcnt(8)
	v_pk_add_f32 v[8:9], v[8:9], v[24:25]
	v_pk_add_f32 v[10:11], v[10:11], v[26:27]
	s_waitcnt vmcnt(7)
	v_pk_add_f32 v[8:9], v[8:9], v[28:29]
	v_pk_add_f32 v[10:11], v[10:11], v[30:31]
	s_waitcnt vmcnt(6)
	v_pk_add_f32 v[8:9], v[8:9], v[32:33]
	v_pk_add_f32 v[10:11], v[10:11], v[34:35]
	s_waitcnt vmcnt(5)
	v_pk_add_f32 v[8:9], v[8:9], v[36:37]
	v_pk_add_f32 v[10:11], v[10:11], v[38:39]
	s_waitcnt vmcnt(4)
	v_pk_add_f32 v[8:9], v[8:9], v[40:41]
	v_pk_add_f32 v[10:11], v[10:11], v[42:43]
	s_waitcnt vmcnt(3)
	v_pk_add_f32 v[8:9], v[8:9], v[44:45]
	v_pk_add_f32 v[10:11], v[10:11], v[46:47]
	s_waitcnt vmcnt(2)
	v_pk_add_f32 v[8:9], v[8:9], v[48:49]
	v_pk_add_f32 v[10:11], v[10:11], v[50:51]
	s_waitcnt vmcnt(1)
	v_lshlrev_b32_e32 v60, 16, v52
	v_and_b32_e32 v61, 0xffff0000, v52
	v_lshlrev_b32_e32 v62, 16, v53
	v_and_b32_e32 v63, 0xffff0000, v53
	s_waitcnt vmcnt(0)
	v_pk_fma_f32 v[8:9], v[8:9], v[56:57], v[60:61]
	v_pk_fma_f32 v[10:11], v[10:11], v[58:59], v[62:63]
	global_store_dwordx4 v1, v[8:11], s[20:21]
